# mixer queue: next item claimed (returning atomic) during the second-to-last KV tile of the current attention item
# baseline (speedup 1.0000x reference)
; DI void phase_mix(const P& p, int l, int rep, char* lds) {
;     ...
;   const int nitems = 64 + 512 + 256 + 256 + (l == 0 ? 128 : 0);
;   const float lam_init = (l == 0) ? 0.2f : (0.8f - 0.6f * 0.7408182206817179f);
;   const float* dl = p.df_lam + l * 128;
;   float d01 = 0.f, d23 = 0.f;
;   for (int i = 0; i < 32; ++i) {
;     d01 += dl[i] * dl[32 + i];
;     d23 += dl[64 + i] * dl[96 + i];
;   }
;   const float lam = expf(d01) - expf(d23) + lam_init;
;   const float* subln = p.df_subln + l * 64;
;   const float cB = 0.125f * LOG2E, cC = 0.17677669529663687f * LOG2E;
.LBB0_812:
	s_andn2_b64 vcc, exec, s[0:1]
	s_cbranch_vccnz .LBB0_941
	s_cmp_gt_u32 s23, 3
	s_cselect_b64 s[0:1], -1, 0
	v_writelane_b32 v255, s0, 52
	v_mov_b32_e32 v0, 0x3eb60549
	v_mov_b32_e32 v130, 0x3e4ccccd
	v_writelane_b32 v255, s1, 53
	s_lshl_b32 s0, s50, 7
	s_ashr_i32 s1, s0, 31
	s_lshl_b64 s[0:1], s[0:1], 2
	s_add_u32 s0, s4, s0
	s_addc_u32 s1, s5, s1
	global_load_dwordx4 v[2:5], v1, s[0:1]
	global_load_dwordx4 v[6:9], v1, s[0:1] offset:128
	global_load_dwordx4 v[10:13], v1, s[0:1] offset:256
	global_load_dwordx4 v[14:17], v1, s[0:1] offset:384
	global_load_dwordx4 v[18:21], v1, s[0:1] offset:16
	global_load_dwordx4 v[22:25], v1, s[0:1] offset:144
	global_load_dwordx4 v[26:29], v1, s[0:1] offset:272
	global_load_dwordx4 v[30:33], v1, s[0:1] offset:400
	global_load_dwordx4 v[34:37], v1, s[0:1] offset:32
	global_load_dwordx4 v[38:41], v1, s[0:1] offset:160
	global_load_dwordx4 v[42:45], v1, s[0:1] offset:288
	global_load_dwordx4 v[46:49], v1, s[0:1] offset:416
	global_load_dwordx4 v[50:53], v1, s[0:1] offset:48
	global_load_dwordx4 v[54:57], v1, s[0:1] offset:176
	global_load_dwordx4 v[58:61], v1, s[0:1] offset:304
	global_load_dwordx4 v[62:65], v1, s[0:1] offset:432
	global_load_dwordx4 v[66:69], v1, s[0:1] offset:64
	global_load_dwordx4 v[70:73], v1, s[0:1] offset:192
	global_load_dwordx4 v[74:77], v1, s[0:1] offset:320
	global_load_dwordx4 v[78:81], v1, s[0:1] offset:448
	global_load_dwordx4 v[82:85], v1, s[0:1] offset:80
	global_load_dwordx4 v[86:89], v1, s[0:1] offset:208
	global_load_dwordx4 v[90:93], v1, s[0:1] offset:336
	global_load_dwordx4 v[94:97], v1, s[0:1] offset:464
	global_load_dwordx4 v[98:101], v1, s[0:1] offset:96
	global_load_dwordx4 v[102:105], v1, s[0:1] offset:224
	global_load_dwordx4 v[106:109], v1, s[0:1] offset:352
	global_load_dwordx4 v[110:113], v1, s[0:1] offset:480
	global_load_dwordx4 v[114:117], v1, s[0:1] offset:112
	global_load_dwordx4 v[118:121], v1, s[0:1] offset:240
	global_load_dwordx4 v[122:125], v1, s[0:1] offset:368
	global_load_dwordx4 v[126:129], v1, s[0:1] offset:496
	s_lshl_b32 s0, s50, 6
	s_ashr_i32 s1, s0, 31
	s_lshl_b64 s[0:1], s[0:1], 2
	s_add_u32 s24, s6, s0
	s_addc_u32 s25, s7, s1
	s_ashr_i32 s51, s50, 31
	s_and_b32 s2, s23, -4
	v_writelane_b32 v255, s24, 54
	s_cmp_lt_u32 s23, 4
	s_cselect_b64 vcc, -1, 0
	v_writelane_b32 v255, s25, 55
	v_writelane_b32 v255, s2, 56
	s_and_b64 s[24:25], vcc, exec
	s_movk_i32 s2, 0x4c0
	s_cselect_b32 s59, s2, 0x440
	s_mov_b32 s2, 0x3fb8aa3b
	s_cselect_b32 s25, 0x9000, s21
	s_lshl_b64 s[26:27], s[50:51], 2
	v_readlane_b32 s40, v255, 24
	v_readlane_b32 s41, v255, 25
	s_add_u32 s26, s40, s26
	v_cndmask_b32_e32 v0, v0, v130, vcc
	s_addc_u32 s27, s41, s27
	s_mov_b32 s99, 0
	s_mov_b32 s23, 0x42b17218
	v_writelane_b32 v255, s26, 57
	v_sub_f32_e32 v227, 1.0, v0
	s_waitcnt vmcnt(30)
	v_fma_f32 v2, v2, v6, 0
	v_fmac_f32_e32 v2, v3, v7
	v_fmac_f32_e32 v2, v4, v8
	v_fmac_f32_e32 v2, v5, v9
	s_waitcnt vmcnt(26)
	v_fmac_f32_e32 v2, v18, v22
	v_fmac_f32_e32 v2, v19, v23
	v_fmac_f32_e32 v2, v20, v24
	v_fmac_f32_e32 v2, v21, v25
	v_fma_f32 v6, v10, v14, 0
	s_waitcnt vmcnt(22)
	v_fmac_f32_e32 v2, v34, v38
	v_fmac_f32_e32 v6, v11, v15
	v_fmac_f32_e32 v2, v35, v39
	v_fmac_f32_e32 v6, v12, v16
	v_fmac_f32_e32 v2, v36, v40
	v_fmac_f32_e32 v6, v13, v17
	v_fmac_f32_e32 v2, v37, v41
	v_fmac_f32_e32 v6, v26, v30
	s_waitcnt vmcnt(18)
	v_fmac_f32_e32 v2, v50, v54
	v_fmac_f32_e32 v6, v27, v31
	v_fmac_f32_e32 v2, v51, v55
	v_fmac_f32_e32 v6, v28, v32
	v_fmac_f32_e32 v2, v52, v56
	v_fmac_f32_e32 v6, v29, v33
	v_fmac_f32_e32 v2, v53, v57
	v_fmac_f32_e32 v6, v42, v46
	s_waitcnt vmcnt(14)
	v_fmac_f32_e32 v2, v66, v70
	v_fmac_f32_e32 v6, v43, v47
	v_fmac_f32_e32 v2, v67, v71
	v_fmac_f32_e32 v6, v44, v48
	v_fmac_f32_e32 v2, v68, v72
	v_fmac_f32_e32 v6, v45, v49
	v_fmac_f32_e32 v2, v69, v73
	v_fmac_f32_e32 v6, v58, v62
	s_waitcnt vmcnt(10)
	v_fmac_f32_e32 v2, v82, v86
	v_fmac_f32_e32 v6, v59, v63
	v_fmac_f32_e32 v2, v83, v87
	v_fmac_f32_e32 v6, v60, v64
	v_fmac_f32_e32 v2, v84, v88
	v_fmac_f32_e32 v6, v61, v65
	v_fmac_f32_e32 v2, v85, v89
	v_fmac_f32_e32 v6, v74, v78
	s_waitcnt vmcnt(6)
	v_fmac_f32_e32 v2, v98, v102
	v_fmac_f32_e32 v6, v75, v79
	v_fmac_f32_e32 v2, v99, v103
	v_fmac_f32_e32 v6, v76, v80
	v_fmac_f32_e32 v2, v100, v104
	v_fmac_f32_e32 v6, v77, v81
	v_fmac_f32_e32 v2, v101, v105
	v_fmac_f32_e32 v6, v90, v94
	s_waitcnt vmcnt(2)
	v_fmac_f32_e32 v2, v114, v118
	v_fmac_f32_e32 v6, v91, v95
	v_fmac_f32_e32 v2, v115, v119
	v_fmac_f32_e32 v6, v92, v96
	v_fmac_f32_e32 v2, v116, v120
	v_fmac_f32_e32 v6, v93, v97
	v_fmac_f32_e32 v2, v117, v121
	v_fmac_f32_e32 v6, v106, v110
	v_mul_f32_e32 v3, 0x3fb8aa3b, v2
	v_fmac_f32_e32 v6, v107, v111
	v_fma_f32 v4, v2, s2, -v3
	v_rndne_f32_e32 v5, v3
	v_fmac_f32_e32 v6, v108, v112
	v_fmac_f32_e32 v4, 0x32a5705f, v2
	v_sub_f32_e32 v3, v3, v5
	v_fmac_f32_e32 v6, v109, v113
	v_add_f32_e32 v3, v3, v4
	s_waitcnt vmcnt(0)
	v_fmac_f32_e32 v6, v122, v126
	v_exp_f32_e32 v3, v3
	v_cvt_i32_f32_e32 v4, v5
	v_fmac_f32_e32 v6, v123, v127
	v_fmac_f32_e32 v6, v124, v128
	v_fmac_f32_e32 v6, v125, v129
	v_ldexp_f32 v3, v3, v4
	v_mul_f32_e32 v4, 0x3fb8aa3b, v6
	v_fma_f32 v5, v6, s2, -v4
	v_rndne_f32_e32 v7, v4
	v_fmac_f32_e32 v5, 0x32a5705f, v6
	v_sub_f32_e32 v4, v4, v7
	v_add_f32_e32 v4, v4, v5
	v_exp_f32_e32 v4, v4
	v_cvt_i32_f32_e32 v5, v7
	s_mov_b32 s2, 0xc2ce8ed0
	v_cmp_ngt_f32_e32 vcc, s2, v2
	v_mov_b32_e32 v7, 0x7f800000
	v_writelane_b32 v255, s27, 58
	v_cndmask_b32_e32 v3, 0, v3, vcc
	v_cmp_nlt_f32_e32 vcc, s23, v2
	v_readlane_b32 s44, v255, 36
	v_readlane_b32 s50, v255, 42
	v_cndmask_b32_e32 v2, v7, v3, vcc
	v_ldexp_f32 v3, v4, v5
	v_cmp_ngt_f32_e32 vcc, s2, v6
	v_readlane_b32 s51, v255, 43
	s_add_u32 s0, s50, s0
	v_cndmask_b32_e32 v3, 0, v3, vcc
	v_cmp_nlt_f32_e32 vcc, s23, v6
	v_readlane_b32 s45, v255, 37
	v_readlane_b32 s46, v255, 38
	v_cndmask_b32_e32 v3, v7, v3, vcc
	v_sub_f32_e32 v2, v2, v3
	v_readlane_b32 s47, v255, 39
	v_readlane_b32 s48, v255, 40
	v_readlane_b32 s49, v255, 41
	s_addc_u32 s1, s51, s1
	v_add_f32_e32 v228, v0, v2
	v_writelane_b32 v255, s59, 59
	s_branch .LBB0_817

; DI int tidx() { int t = threadIdx.x; asm volatile("" : "+v"(t)); return t; }
; DI void phase_mix(const P& p, int l, int rep, char* lds) {
;     ...
;   while (true) {
;     if (tidx() == 0) s_item = atomicAdd(&p.ctr[l + 2 * rep], 1);
;     __syncthreads();
;     int it = __builtin_amdgcn_readfirstlane(s_item);
.LBB0_817:
	v_mov_b32_e32 v0, v195
	s_nop 0
	v_cmp_eq_u32_e32 vcc, 0, v0
	s_and_saveexec_b64 s[40:41], vcc
	s_cbranch_execz .LBB0_821
	s_cmp_eq_u32 s99, 0
	s_cbranch_scc1 .Lpf_orig
	ds_write_b32 v1, v239 offset:16
	s_branch .LBB0_821
.Lpf_orig:
	s_mov_b64 s[44:45], exec
	v_mbcnt_lo_u32_b32 v0, s44, 0
	v_mbcnt_hi_u32_b32 v0, s45, v0
	v_cmp_eq_u32_e32 vcc, 0, v0
	s_and_saveexec_b64 s[42:43], vcc
	s_cbranch_execz .LBB0_820
	s_bcnt1_i32_b64 s2, s[44:45]
	v_readlane_b32 s26, v255, 57
	v_mov_b32_e32 v2, s2
	v_readlane_b32 s27, v255, 58
	s_nop 4
	global_atomic_add v2, v1, v2, s[26:27] sc0

; DI int tidx() { int t = threadIdx.x; asm volatile("" : "+v"(t)); return t; }
; DI void phase_mix(const P& p, int l, int rep, char* lds) {
;     ...
;     if (tidx() == 0) s_item = atomicAdd(&p.ctr[l + 2 * rep], 1);
;     __syncthreads();
;     int it = __builtin_amdgcn_readfirstlane(s_item);
;     __syncthreads();
;     if (it >= nitems) break;
;     if (it < 64) {
;       hgrn_unit(p, l, it, lds);
;       continue;
;     }
;     it -= 64;
;     int mode, b, hq, qb, sq0, sq1, sk, sv, qtok0, ka0, na, kb0 = 2048, nb = 0, yrow0, ycol0;
;     bool window = false, has_sink = false, isctx = false;
;     int kind;
;     if (it < 512) { kind = 0; b = it >> 5; hq = (it >> 3) & 3; qb = it & 7; }
;     else if (it < 768) { it -= 512; kind = 1; b = it >> 4; hq = (it >> 3) & 1; qb = it & 7; }
;     else if (it < 1024) { it -= 768; kind = 2; b = it >> 4; hq = (it >> 3) & 1; qb = it & 7; }
;     else if (it < 1088) { it -= 1024; kind = 0; isctx = true; b = it >> 2; hq = it & 3; qb = 0; }
;     else if (it < 1120) { it -= 1088; kind = 1; isctx = true; b = it >> 1; hq = it & 1; qb = 0; }
;     else { it -= 1120; kind = 2; isctx = true; b = it >> 1; hq = it & 1; qb = 0; }
.LBB0_821:
	s_or_b64 exec, exec, s[40:41]
	s_mov_b32 s99, 0
	s_waitcnt lgkmcnt(0)
	s_barrier
	ds_read_b32 v0, v1 offset:16
	s_mov_b64 s[40:41], -1
	s_waitcnt lgkmcnt(0)
	s_barrier
	v_readfirstlane_b32 s26, v0
	s_cmp_ge_i32 s26, s59
	s_cbranch_scc1 .LBB0_816
	s_cmp_gt_i32 s26, 63
	s_cbranch_scc0 .LBB0_899
	s_cmpk_gt_u32 s26, 0x23f
	s_mov_b64 s[44:45], -1
	s_cbranch_scc0 .LBB0_840
	s_cmpk_gt_u32 s26, 0x33f
	s_cbranch_scc0 .LBB0_837
	s_mov_b64 s[46:47], -1
	s_cmpk_gt_u32 s26, 0x43f
	s_cbranch_scc0 .LBB0_834
	s_cmpk_gt_u32 s26, 0x47f
	s_mov_b64 s[40:41], -1
	s_cbranch_scc0 .LBB0_832
	s_cmpk_gt_u32 s26, 0x49f
	s_mov_b64 s[42:43], -1
	s_cbranch_scc0 .LBB0_829
	s_add_i32 s2, s26, 0xfffffb60
	s_lshr_b32 s2, s2, 1
	s_mov_b64 s[44:45], 0

; template <int MODE> ...
;     ...
;   for (int it = 0; it < ntile; ++it) {
;     const int kt0 = (it < na) ? ka0 + it * 64 : kb0 + (it - na) * 64;
;     const bool masked = window && (it < na);
;     const u16* Ks = Kbase + (it & 1) * (2 * 64 * 64);
;     const u16* Vs = Ks + 64 * 64;
;     __syncthreads();
;     const bool more = it + 1 < ntile;
;     if (more) {
;       const int kn = (it + 1 < na) ? ka0 + (it + 1) * 64 : kb0 + (it + 1 - na) * 64;
;       ALOAD(kn)
;     }
.LBB0_862:
	s_add_i32 s66, s58, 1
	s_cmp_lt_i32 s66, s45
	s_cselect_b64 s[56:57], -1, 0
	s_waitcnt lgkmcnt(0)
	s_barrier
	s_add_i32 s98, s2, 0xffffe000
	s_and_b32 s98, s98, 0x2000
	v_lshl_add_u32 v0, s98, 1, v233
	v_add_u32_e32 v234, v0, v230
	v_add_u32_e32 v0, v0, v231
	ds_read_b128 v[108:111], v234
	ds_read_b128 v[112:115], v234 offset:2048
	ds_read_b128 v[120:123], v0
	ds_read_b128 v[132:135], v0 offset:2048
	s_cmp_ge_i32 s66, s45
	s_cbranch_scc1 .LBB0_864
	s_cmp_lt_i32 s66, s63
	s_cselect_b32 s59, 0, s63
	s_cselect_b32 s60, s64, 0x800
	s_lshl_b32 s59, s59, 6
	s_sub_i32 s59, s60, s59
	s_add_i32 s60, s65, s59
	s_ashr_i32 s61, s60, 31
	s_lshl_b64 s[68:69], s[60:61], 7
	s_waitcnt vmcnt(1)
	v_lshl_add_u64 v[100:101], v[182:183], 0, s[68:69]
	s_waitcnt vmcnt(0)
	v_lshl_add_u64 v[104:105], s[60:61], 1, v[184:185]
	global_load_dwordx4 v[100:103], v[100:101], off
	s_nop 0
	global_load_dwordx4 v[104:107], v[104:105], off
	s_add_i32 s100, s58, 2
	s_cmp_lg_u32 s100, s45
	s_cbranch_scc1 .Lpf0_skip
	s_mov_b32 s99, 1
	v_cmp_eq_u32_e32 vcc, 0, v195
	s_and_saveexec_b64 s[100:101], vcc
	s_cbranch_execz .Lpf0_rest
	v_readlane_b32 s68, v255, 57
	v_readlane_b32 s69, v255, 58
	v_mov_b32_e32 v235, 1
	s_nop 3
	global_atomic_add v239, v1, v235, s[68:69] sc0
.Lpf0_rest:
	s_or_b64 exec, exec, s[100:101]
.Lpf0_skip:
.LBB0_864:
	s_cmp_lt_i32 s58, s63
	s_cselect_b64 s[58:59], -1, 0
	s_and_b64 s[60:61], s[58:59], exec
	s_cselect_b32 s60, 0, s63
	s_cselect_b32 s61, s64, 0x800
	s_lshl_b32 s60, s60, 6
	s_and_b64 s[58:59], s[46:47], s[58:59]
	s_sub_i32 s67, s61, s60
	s_xor_b64 s[60:61], s[58:59], -1
	s_and_b64 vcc, exec, s[60:61]
	s_cbranch_vccnz .LBB0_868
	v_readfirstlane_b32 s61, v181
	s_lshl_b32 s61, s61, 5
	s_add_i32 s68, s65, s67
	s_add_i32 s69, s61, s62
	s_sub_i32 s60, s68, 64
	s_add_i32 s61, s69, 0x9f
	s_cmp_le_i32 s60, s61
	s_cselect_b64 s[60:61], -1, 0
	s_add_i32 s68, s68, -1
	s_addk_i32 s69, 0xff80
	s_cmp_ge_i32 s68, s69
	s_cselect_b64 s[68:69], -1, 0
	s_and_b64 s[60:61], s[60:61], s[68:69]
	s_andn2_b64 vcc, exec, s[60:61]
	s_cbranch_vccz .LBB0_869

; template <int MODE> ...
;     ...
;   for (int it = 0; it < ntile; ++it) {
;     const int kt0 = (it < na) ? ka0 + it * 64 : kb0 + (it - na) * 64;
;     const bool masked = window && (it < na);
;     const u16* Ks = Kbase + (it & 1) * (2 * 64 * 64);
;     const u16* Vs = Ks + 64 * 64;
;     __syncthreads();
;     const bool more = it + 1 < ntile;
;     if (more) {
;       const int kn = (it + 1 < na) ? ka0 + (it + 1) * 64 : kb0 + (it + 1 - na) * 64;
;       ALOAD(kn)
;     }
.LBB0_882:
	s_add_i32 s54, s50, 1
	s_cmp_lt_i32 s54, s24
	s_cselect_b64 s[48:49], -1, 0
	s_waitcnt lgkmcnt(0)
	s_barrier
	s_add_i32 s98, s2, 0xffffe000
	s_and_b32 s98, s98, 0x2000
	v_lshl_add_u32 v98, s98, 1, v196
	v_add_u32_e32 v198, v98, v191
	v_add_u32_e32 v197, v98, v192
	ds_read_b128 v[90:93], v198
	ds_read_b128 v[94:97], v198 offset:2048
	ds_read_b128 v[98:101], v197
	ds_read_b128 v[102:105], v197 offset:2048
	s_cmp_ge_i32 s54, s24
	s_cbranch_scc1 .LBB0_884
	s_cmp_lt_i32 s54, s63
	s_cselect_b32 s51, 0, s63
	s_cselect_b32 s52, s64, 0x800
	s_lshl_b32 s51, s51, 6
	s_sub_i32 s51, s52, s51
	s_add_i32 s52, s45, s51
	s_ashr_i32 s53, s52, 31
	s_lshl_b64 s[56:57], s[52:53], 7
	s_waitcnt vmcnt(1)
	v_lshl_add_u64 v[50:51], v[166:167], 0, s[56:57]
	s_waitcnt vmcnt(0)
	v_lshl_add_u64 v[54:55], s[52:53], 1, v[168:169]
	global_load_dwordx4 v[50:53], v[50:51], off
	s_nop 0
	global_load_dwordx4 v[54:57], v[54:55], off
	s_add_i32 s100, s50, 2
	s_cmp_lg_u32 s100, s24
	s_cbranch_scc1 .Lpf1_skip
	s_mov_b32 s99, 1
	v_cmp_eq_u32_e32 vcc, 0, v195
	s_and_saveexec_b64 s[100:101], vcc
	s_cbranch_execz .Lpf1_rest
	v_readlane_b32 s56, v255, 57
	v_readlane_b32 s57, v255, 58
	v_mov_b32_e32 v235, 1
	s_nop 3
	global_atomic_add v239, v1, v235, s[56:57] sc0

; template <int MODE> ...
;     ...
;     bool skip = false;
;     if (masked) {
;       const int qlo = qtok0 + __builtin_amdgcn_readfirstlane(w) * 32;
;       skip = (kt0 > qlo + 31 + 128) || (kt0 + 63 < qlo - 128);
;     }
.Lpf1_skip:
.LBB0_884:
	s_cmp_lt_i32 s50, s63
	s_cselect_b64 s[50:51], -1, 0
	s_and_b64 s[52:53], s[50:51], exec
	s_cselect_b32 s52, 0, s63
	s_cselect_b32 s53, s64, 0x800
	s_lshl_b32 s52, s52, 6
	s_and_b64 s[50:51], s[46:47], s[50:51]
	s_sub_i32 s55, s53, s52
	s_xor_b64 s[52:53], s[50:51], -1
	s_and_b64 vcc, exec, s[52:53]
	s_cbranch_vccnz .LBB0_888
	v_readfirstlane_b32 s53, v163
	s_lshl_b32 s53, s53, 5
	s_add_i32 s56, s45, s55
	s_add_i32 s57, s53, s62
	s_sub_i32 s52, s56, 64
	s_add_i32 s53, s57, 0x9f
	s_cmp_le_i32 s52, s53
	s_cselect_b64 s[52:53], -1, 0
	s_add_i32 s56, s56, -1
	s_addk_i32 s57, 0xff80
	s_cmp_ge_i32 s56, s57
	s_cselect_b64 s[56:57], -1, 0
	s_and_b64 s[52:53], s[52:53], s[56:57]
	s_andn2_b64 vcc, exec, s[52:53]
	s_cbranch_vccz .LBB0_889
